# GEMM K-loop heads (both GEMM phases) aligned to 64 B
# baseline (speedup 1.0000x reference)
; template <class Epi>
; __device__ __forceinline__ void gemm_phase(LAS unsigned char* lds, const Gemm g, const StaticOrder& S, const Epi& E) {
;     ...
;         const bool has_next = S.next(ui + 1, nxt);
;         const char* nA = has_next ? (const char*)g.A + (size_t)nxt.pm * tstep : cA; const char* nB = has_next ? (const char*)g.Bt + (size_t)nxt.pn * tstep : cB;
;         for (int t = 0; t < nt; t += 2) {
;             const bool last = (t == nt - 2);
;             const char* a1 = cA + (size_t)(t + 1) * kstep;
;             const char* a2 = last ? nA : cA + (size_t)(t + 2) * kstep; const char* b2 = last ? nB : cB + (size_t)(t + 2) * kstep;
;             const char* a3 = a2 + kstep; const char* b3 = b2 + kstep;
;             PG8_LDB(B0, 0, 0); PG8_SCHED; PG8_LDA(At, 0, 0); PG8_STAGE(PG8_SA(1, 1), a1 + hstep, voffA);
;             PG8_WAIT_L(8); PG8_BAR; PG8_WAIT_L(0); PG8_MMA(0, 0, At, B0); PG8_BAR; PG8_SCHED;
;             PG8_LDB(B1, 0, 1); PG8_STAGE(PG8_SB(0, 0), b2, voffB);
;             PG8_BAR; PG8_WAIT_L(0); PG8_MMA(0, 1, At, B1); PG8_BAR;
;             PG8_LDA(At, 0, 1); PG8_STAGE(PG8_SA(0, 0), a2, voffA);
;             PG8_BAR; PG8_WAIT_L(0); PG8_MMA(1, 0, At, B0); PG8_BAR; PG8_SCHED;
;             PG8_STAGE(PG8_SB(0, 1), b2 + hstep, voffB);
;             PG8_WAIT_V(6); PG8_BAR; PG8_MMA(1, 1, At, B1); PG8_BAR;
;             PG8_LDB(B0, 1, 0); PG8_SCHED; PG8_LDA(At, 1, 0); PG8_STAGE(PG8_SA(0, 1), a2 + hstep, voffA);
;             PG8_WAIT_L(8); PG8_BAR; PG8_WAIT_L(0); PG8_MMA(0, 0, At, B0); PG8_BAR; PG8_SCHED;
;             PG8_LDB(B1, 1, 1); PG8_STAGE(PG8_SB(1, 0), b3, voffB);
;             PG8_BAR; PG8_WAIT_L(0); PG8_MMA(0, 1, At, B1); PG8_BAR;
;             PG8_LDA(At, 1, 1); PG8_STAGE(PG8_SA(1, 0), a3, voffA);
;             PG8_BAR; PG8_WAIT_L(0); PG8_MMA(1, 0, At, B0); PG8_BAR; PG8_SCHED;
;             PG8_STAGE(PG8_SB(1, 1), b3 + hstep, voffB);
;             PG8_WAIT_V(6); PG8_BAR; PG8_MMA(1, 1, At, B1); PG8_BAR;
;         }
;         E(acc, cur, wr, wc, fr, fq);
;         if (!has_next) break;
; #pragma unroll
;         for (int a = 0; a < 2; ++a)
; #pragma unroll
;             for (int b = 0; b < 2; ++b)
; #pragma unroll
;                 for (int m = 0; m < 4; ++m)
; #pragma unroll
;                     for (int n = 0; n < 2; ++n) acc[a][b][m][n] = (f32x4){0.f, 0.f, 0.f, 0.f};
;         cur = nxt; cA = nA; cB = nB; ++ui;
.LBB0_79:
	s_ashr_i32 s7, s6, 31
	v_cmp_lt_i64_e32 vcc, s[18:19], v[150:151]
	s_lshl_b64 s[18:19], s[6:7], 20
	s_add_u32 s20, s2, s18
	s_addc_u32 s21, s3, s19
	s_and_b64 s[18:19], vcc, exec
	s_cselect_b32 s7, s21, s13
	s_cselect_b32 s63, s20, s12
	s_ashr_i32 s25, s24, 31
	s_lshl_b64 s[18:19], s[24:25], 20
	s_add_u32 s18, s4, s18
	s_addc_u32 s19, s5, s19
	s_and_b64 s[28:29], vcc, exec
	s_cselect_b32 s25, s19, s27
	s_cselect_b32 s64, s18, s26
	s_add_u32 s12, s12, 0x80080
	s_addc_u32 s13, s13, 0
	s_add_u32 s65, s26, 0x100
	v_mov_b32_e32 v0, 0
	s_addc_u32 s66, s27, 0
	s_mov_b32 s67, -2
	v_mov_b32_e32 v1, v0
	v_mov_b32_e32 v2, v0
	v_mov_b32_e32 v3, v0
	v_mov_b32_e32 v4, v0
	v_mov_b32_e32 v5, v0
	v_mov_b32_e32 v6, v0
	v_mov_b32_e32 v7, v0
	v_mov_b32_e32 v16, v0
	v_mov_b32_e32 v17, v0
	v_mov_b32_e32 v18, v0
	v_mov_b32_e32 v19, v0
	v_mov_b32_e32 v20, v0
	v_mov_b32_e32 v21, v0
	v_mov_b32_e32 v22, v0
	v_mov_b32_e32 v23, v0
	v_mov_b32_e32 v24, v0
	v_mov_b32_e32 v25, v0
	v_mov_b32_e32 v26, v0
	v_mov_b32_e32 v27, v0
	v_mov_b32_e32 v28, v0
	v_mov_b32_e32 v29, v0
	v_mov_b32_e32 v30, v0
	v_mov_b32_e32 v31, v0
	v_mov_b32_e32 v40, v0
	v_mov_b32_e32 v41, v0
	v_mov_b32_e32 v42, v0
	v_mov_b32_e32 v43, v0
	v_mov_b32_e32 v44, v0
	v_mov_b32_e32 v45, v0
	v_mov_b32_e32 v46, v0
	v_mov_b32_e32 v47, v0
	v_mov_b32_e32 v8, v0
	v_mov_b32_e32 v9, v0
	v_mov_b32_e32 v10, v0
	v_mov_b32_e32 v11, v0
	v_mov_b32_e32 v12, v0
	v_mov_b32_e32 v13, v0
	v_mov_b32_e32 v14, v0
	v_mov_b32_e32 v15, v0
	v_mov_b32_e32 v32, v0
	v_mov_b32_e32 v33, v0
	v_mov_b32_e32 v34, v0
	v_mov_b32_e32 v35, v0
	v_mov_b32_e32 v36, v0
	v_mov_b32_e32 v37, v0
	v_mov_b32_e32 v38, v0
	v_mov_b32_e32 v39, v0
	v_mov_b32_e32 v48, v0
	v_mov_b32_e32 v49, v0
	v_mov_b32_e32 v50, v0
	v_mov_b32_e32 v51, v0
	v_mov_b32_e32 v52, v0
	v_mov_b32_e32 v53, v0
	v_mov_b32_e32 v54, v0
	v_mov_b32_e32 v55, v0
	v_mov_b32_e32 v56, v0
	v_mov_b32_e32 v57, v0
	v_mov_b32_e32 v58, v0
	v_mov_b32_e32 v59, v0
	v_mov_b32_e32 v60, v0
	v_mov_b32_e32 v61, v0
	v_mov_b32_e32 v62, v0
	v_mov_b32_e32 v63, v0
	v_mov_b32_e32 v64, v0
	v_mov_b32_e32 v65, v0
	v_mov_b32_e32 v66, v0
	v_mov_b32_e32 v67, v0
	v_mov_b32_e32 v68, v0
	v_mov_b32_e32 v69, v0
	v_mov_b32_e32 v70, v0
	v_mov_b32_e32 v71, v0
	v_mov_b32_e32 v80, v0
	v_mov_b32_e32 v81, v0
	v_mov_b32_e32 v82, v0
	v_mov_b32_e32 v83, v0
	v_mov_b32_e32 v84, v0
	v_mov_b32_e32 v85, v0
	v_mov_b32_e32 v86, v0
	v_mov_b32_e32 v87, v0
	v_mov_b32_e32 v88, v0
	v_mov_b32_e32 v89, v0
	v_mov_b32_e32 v90, v0
	v_mov_b32_e32 v91, v0
	v_mov_b32_e32 v92, v0
	v_mov_b32_e32 v93, v0
	v_mov_b32_e32 v94, v0
	v_mov_b32_e32 v95, v0
	v_mov_b32_e32 v104, v0
	v_mov_b32_e32 v105, v0
	v_mov_b32_e32 v106, v0
	v_mov_b32_e32 v107, v0
	v_mov_b32_e32 v108, v0
	v_mov_b32_e32 v109, v0
	v_mov_b32_e32 v110, v0
	v_mov_b32_e32 v111, v0
	v_mov_b32_e32 v72, v0
	v_mov_b32_e32 v73, v0
	v_mov_b32_e32 v74, v0
	v_mov_b32_e32 v75, v0
	v_mov_b32_e32 v76, v0
	v_mov_b32_e32 v77, v0
	v_mov_b32_e32 v78, v0
	v_mov_b32_e32 v79, v0
	v_mov_b32_e32 v96, v0
	v_mov_b32_e32 v97, v0
	v_mov_b32_e32 v98, v0
	v_mov_b32_e32 v99, v0
	v_mov_b32_e32 v100, v0
	v_mov_b32_e32 v101, v0
	v_mov_b32_e32 v102, v0
	v_mov_b32_e32 v103, v0
	v_mov_b32_e32 v112, v0
	v_mov_b32_e32 v113, v0
	v_mov_b32_e32 v114, v0
	v_mov_b32_e32 v115, v0
	v_mov_b32_e32 v116, v0
	v_mov_b32_e32 v117, v0
	v_mov_b32_e32 v118, v0
	v_mov_b32_e32 v119, v0
	v_mov_b32_e32 v120, v0
	v_mov_b32_e32 v121, v0
	v_mov_b32_e32 v122, v0
	v_mov_b32_e32 v123, v0
	v_mov_b32_e32 v124, v0
	v_mov_b32_e32 v125, v0
	v_mov_b32_e32 v126, v0
	v_mov_b32_e32 v127, v0
	.p2align 6

; template <class Epi>
; __device__ __forceinline__ void gemm_phase(LAS unsigned char* lds, const Gemm g, const StaticOrder& S, const Epi& E) {
;     ...
;         const bool has_next = S.next(ui + 1, nxt);
;         const char* nA = has_next ? (const char*)g.A + (size_t)nxt.pm * tstep : cA; const char* nB = has_next ? (const char*)g.Bt + (size_t)nxt.pn * tstep : cB;
;         for (int t = 0; t < nt; t += 2) {
;             const bool last = (t == nt - 2);
;             const char* a1 = cA + (size_t)(t + 1) * kstep;
;             const char* a2 = last ? nA : cA + (size_t)(t + 2) * kstep; const char* b2 = last ? nB : cB + (size_t)(t + 2) * kstep;
;             const char* a3 = a2 + kstep; const char* b3 = b2 + kstep;
;             PG8_LDB(B0, 0, 0); PG8_SCHED; PG8_LDA(At, 0, 0); PG8_STAGE(PG8_SA(1, 1), a1 + hstep, voffA);
;             PG8_WAIT_L(8); PG8_BAR; PG8_WAIT_L(0); PG8_MMA(0, 0, At, B0); PG8_BAR; PG8_SCHED;
;             PG8_LDB(B1, 0, 1); PG8_STAGE(PG8_SB(0, 0), b2, voffB);
;             PG8_BAR; PG8_WAIT_L(0); PG8_MMA(0, 1, At, B1); PG8_BAR;
;             PG8_LDA(At, 0, 1); PG8_STAGE(PG8_SA(0, 0), a2, voffA);
;             PG8_BAR; PG8_WAIT_L(0); PG8_MMA(1, 0, At, B0); PG8_BAR; PG8_SCHED;
;             PG8_STAGE(PG8_SB(0, 1), b2 + hstep, voffB);
;             PG8_WAIT_V(6); PG8_BAR; PG8_MMA(1, 1, At, B1); PG8_BAR;
;             PG8_LDB(B0, 1, 0); PG8_SCHED; PG8_LDA(At, 1, 0); PG8_STAGE(PG8_SA(0, 1), a2 + hstep, voffA);
;             PG8_WAIT_L(8); PG8_BAR; PG8_WAIT_L(0); PG8_MMA(0, 0, At, B0); PG8_BAR; PG8_SCHED;
;             PG8_LDB(B1, 1, 1); PG8_STAGE(PG8_SB(1, 0), b3, voffB);
;             PG8_BAR; PG8_WAIT_L(0); PG8_MMA(0, 1, At, B1); PG8_BAR;
;             PG8_LDA(At, 1, 1); PG8_STAGE(PG8_SA(1, 0), a3, voffA);
;             PG8_BAR; PG8_WAIT_L(0); PG8_MMA(1, 0, At, B0); PG8_BAR; PG8_SCHED;
;             PG8_STAGE(PG8_SB(1, 1), b3 + hstep, voffB);
;             PG8_WAIT_V(6); PG8_BAR; PG8_MMA(1, 1, At, B1); PG8_BAR;
;         }
;         E(acc, cur, wr, wc, fr, fq);
;         if (!has_next) break;
; #pragma unroll
;         for (int a = 0; a < 2; ++a)
; #pragma unroll
;             for (int b = 0; b < 2; ++b)
; #pragma unroll
;                 for (int m = 0; m < 4; ++m)
; #pragma unroll
;                     for (int n = 0; n < 2; ++n) acc[a][b][m][n] = (f32x4){0.f, 0.f, 0.f, 0.f};
;         cur = nxt; cA = nA; cB = nB; ++ui;
.LBB0_558:
	s_ashr_i32 s25, s24, 31
	v_cmp_lt_i64_e32 vcc, s[26:27], v[146:147]
	s_lshl_b64 s[26:27], s[24:25], 20
	s_add_u32 s26, s2, s26
	s_addc_u32 s27, s3, s27
	s_and_b64 s[28:29], vcc, exec
	s_cselect_b32 s25, s27, s31
	s_cselect_b32 s61, s26, s30
	s_ashr_i32 s23, s22, 31
	s_lshl_b64 s[28:29], s[22:23], 20
	s_add_u32 s28, s4, s28
	s_addc_u32 s29, s5, s29
	s_and_b64 s[40:41], vcc, exec
	s_cselect_b32 s23, s29, s35
	s_cselect_b32 s62, s28, s34
	s_add_u32 s30, s30, 0x80080
	s_addc_u32 s31, s31, 0
	s_add_u32 s63, s34, 0x100
	v_mov_b32_e32 v0, 0
	s_addc_u32 s64, s35, 0
	s_mov_b32 s65, -2
	v_mov_b32_e32 v1, v0
	v_mov_b32_e32 v2, v0
	v_mov_b32_e32 v3, v0
	v_mov_b32_e32 v4, v0
	v_mov_b32_e32 v5, v0
	v_mov_b32_e32 v6, v0
	v_mov_b32_e32 v7, v0
	v_mov_b32_e32 v8, v0
	v_mov_b32_e32 v9, v0
	v_mov_b32_e32 v10, v0
	v_mov_b32_e32 v11, v0
	v_mov_b32_e32 v12, v0
	v_mov_b32_e32 v13, v0
	v_mov_b32_e32 v14, v0
	v_mov_b32_e32 v15, v0
	v_mov_b32_e32 v24, v0
	v_mov_b32_e32 v25, v0
	v_mov_b32_e32 v26, v0
	v_mov_b32_e32 v27, v0
	v_mov_b32_e32 v28, v0
	v_mov_b32_e32 v29, v0
	v_mov_b32_e32 v30, v0
	v_mov_b32_e32 v31, v0
	v_mov_b32_e32 v40, v0
	v_mov_b32_e32 v41, v0
	v_mov_b32_e32 v42, v0
	v_mov_b32_e32 v43, v0
	v_mov_b32_e32 v44, v0
	v_mov_b32_e32 v45, v0
	v_mov_b32_e32 v46, v0
	v_mov_b32_e32 v47, v0
	v_mov_b32_e32 v16, v0
	v_mov_b32_e32 v17, v0
	v_mov_b32_e32 v18, v0
	v_mov_b32_e32 v19, v0
	v_mov_b32_e32 v20, v0
	v_mov_b32_e32 v21, v0
	v_mov_b32_e32 v22, v0
	v_mov_b32_e32 v23, v0
	v_mov_b32_e32 v32, v0
	v_mov_b32_e32 v33, v0
	v_mov_b32_e32 v34, v0
	v_mov_b32_e32 v35, v0
	v_mov_b32_e32 v36, v0
	v_mov_b32_e32 v37, v0
	v_mov_b32_e32 v38, v0
	v_mov_b32_e32 v39, v0
	v_mov_b32_e32 v48, v0
	v_mov_b32_e32 v49, v0
	v_mov_b32_e32 v50, v0
	v_mov_b32_e32 v51, v0
	v_mov_b32_e32 v52, v0
	v_mov_b32_e32 v53, v0
	v_mov_b32_e32 v54, v0
	v_mov_b32_e32 v55, v0
	v_mov_b32_e32 v56, v0
	v_mov_b32_e32 v57, v0
	v_mov_b32_e32 v58, v0
	v_mov_b32_e32 v59, v0
	v_mov_b32_e32 v60, v0
	v_mov_b32_e32 v61, v0
	v_mov_b32_e32 v62, v0
	v_mov_b32_e32 v63, v0
	v_mov_b32_e32 v64, v0
	v_mov_b32_e32 v65, v0
	v_mov_b32_e32 v66, v0
	v_mov_b32_e32 v67, v0
	v_mov_b32_e32 v68, v0
	v_mov_b32_e32 v69, v0
	v_mov_b32_e32 v70, v0
	v_mov_b32_e32 v71, v0
	v_mov_b32_e32 v72, v0
	v_mov_b32_e32 v73, v0
	v_mov_b32_e32 v74, v0
	v_mov_b32_e32 v75, v0
	v_mov_b32_e32 v76, v0
	v_mov_b32_e32 v77, v0
	v_mov_b32_e32 v78, v0
	v_mov_b32_e32 v79, v0
	v_mov_b32_e32 v88, v0
	v_mov_b32_e32 v89, v0
	v_mov_b32_e32 v90, v0
	v_mov_b32_e32 v91, v0
	v_mov_b32_e32 v92, v0
	v_mov_b32_e32 v93, v0
	v_mov_b32_e32 v94, v0
	v_mov_b32_e32 v95, v0
	v_mov_b32_e32 v104, v0
	v_mov_b32_e32 v105, v0
	v_mov_b32_e32 v106, v0
	v_mov_b32_e32 v107, v0
	v_mov_b32_e32 v108, v0
	v_mov_b32_e32 v109, v0
	v_mov_b32_e32 v110, v0
	v_mov_b32_e32 v111, v0
	v_mov_b32_e32 v80, v0
	v_mov_b32_e32 v81, v0
	v_mov_b32_e32 v82, v0
	v_mov_b32_e32 v83, v0
	v_mov_b32_e32 v84, v0
	v_mov_b32_e32 v85, v0
	v_mov_b32_e32 v86, v0
	v_mov_b32_e32 v87, v0
	v_mov_b32_e32 v96, v0
	v_mov_b32_e32 v97, v0
	v_mov_b32_e32 v98, v0
	v_mov_b32_e32 v99, v0
	v_mov_b32_e32 v100, v0
	v_mov_b32_e32 v101, v0
	v_mov_b32_e32 v102, v0
	v_mov_b32_e32 v103, v0
	v_mov_b32_e32 v112, v0
	v_mov_b32_e32 v113, v0
	v_mov_b32_e32 v114, v0
	v_mov_b32_e32 v115, v0
	v_mov_b32_e32 v116, v0
	v_mov_b32_e32 v117, v0
	v_mov_b32_e32 v118, v0
	v_mov_b32_e32 v119, v0
	v_mov_b32_e32 v120, v0
	v_mov_b32_e32 v121, v0
	v_mov_b32_e32 v122, v0
	v_mov_b32_e32 v123, v0
	v_mov_b32_e32 v124, v0
	v_mov_b32_e32 v125, v0
	v_mov_b32_e32 v126, v0
	v_mov_b32_e32 v127, v0
	.p2align 6
